# w_in and q epilogues: rstd loads deserialized; conv-module gating loop unrolled 6x with all 12 loads issued before compute
# speedup vs baseline: 1.0264x; 1.0052x over previous
.LBB7_526:
	v_lshl_add_u32 v192, s28, 8, v143
	v_ashrrev_i32_e32 v193, 31, v192
	v_lshlrev_b64 v[192:193], 6, v[192:193]
	v_lshl_add_u64 v[192:193], v[144:145], 0, v[192:193]
	global_load_dwordx4 v[204:207], v[192:193], off offset:1024
	global_load_dwordx4 v[208:211], v[192:193], off offset:2048
	global_load_dwordx4 v[212:215], v[192:193], off offset:3072
	v_add_co_u32_e32 v192, vcc, 0x2000, v192
	s_nop 1
	v_addc_co_u32_e32 v193, vcc, 0, v193, vcc
	global_load_dwordx4 v[216:219], v[192:193], off
	global_load_dwordx4 v[220:223], v[192:193], off offset:1024
	global_load_dwordx4 v[224:227], v[192:193], off offset:2048
	global_load_dwordx4 v[228:231], v[192:193], off offset:3072
	v_and_b32_e32 v130, 64, v163
	v_xor_b32_e32 v0, 16, v163
	v_add_u32_e32 v130, 64, v130
	v_cmp_lt_i32_e32 vcc, v0, v130
	v_lshl_add_u32 v184, s28, 8, v143
	v_ashrrev_i32_e32 v185, 31, v184
	v_cndmask_b32_e32 v0, v163, v0, vcc
	v_lshlrev_b32_e32 v191, 2, v0
	v_xor_b32_e32 v0, 32, v163
	v_cmp_lt_i32_e32 vcc, v0, v130
	v_lshlrev_b64 v[130:131], 6, v[184:185]
	v_lshl_add_u64 v[130:131], v[144:145], 0, v[130:131]
	global_load_dwordx4 v[130:133], v[130:131], off
	v_or_b32_e32 v180, 16, v184
	v_ashrrev_i32_e32 v181, 31, v180
	v_cndmask_b32_e32 v0, v163, v0, vcc
	v_lshlrev_b32_e32 v0, 2, v0
	v_or_b32_e32 v178, 32, v184
	v_ashrrev_i32_e32 v179, 31, v178
	v_or_b32_e32 v158, 48, v184
	v_ashrrev_i32_e32 v159, 31, v158
	v_add_u32_e32 v156, 0x80, v184
	v_ashrrev_i32_e32 v157, 31, v156
	v_add_u32_e32 v154, 0x90, v184
	v_ashrrev_i32_e32 v155, 31, v154
	s_lshl_b32 s13, s10, 8
	s_or_b32 s10, s13, s31
	s_movk_i32 s15, 0x17f
	v_lshlrev_b64 v[192:193], 11, v[184:185]
	s_waitcnt vmcnt(0)
	v_mov_b32_e32 v150, v131
	v_mov_b32_e32 v151, v132
	v_mov_b32_e32 v131, v133
	v_pk_add_f32 v[150:151], v[150:151], v[130:131]
	v_lshlrev_b64 v[130:131], 6, v[180:181]
	v_lshl_add_u64 v[130:131], v[144:145], 0, v[130:131]
	v_mov_b64_e32 v[130:131], v[204:205]
	v_mov_b64_e32 v[132:133], v[206:207]
	v_mov_b32_e32 v152, v131
	v_mov_b32_e32 v153, v132
	v_mov_b32_e32 v131, v133
	v_pk_add_f32 v[130:131], v[152:153], v[130:131]
	v_mov_b32_e32 v133, v150
	v_mov_b32_e32 v132, v130
	v_mov_b32_e32 v150, v131
	v_pk_add_f32 v[130:131], v[132:133], v[150:151]
	ds_bpermute_b32 v133, v191, v131
	ds_bpermute_b32 v132, v191, v130
	s_waitcnt lgkmcnt(0)
	v_pk_add_f32 v[130:131], v[130:131], v[132:133]
	ds_bpermute_b32 v133, v0, v131
	ds_bpermute_b32 v132, v0, v130
	s_waitcnt lgkmcnt(0)
	v_pk_add_f32 v[130:131], v[130:131], v[132:133]
	s_nop 0
	v_pk_fma_f32 v[188:189], v[130:131], s[26:27], v[162:163] op_sel_hi:[1,0,0]
	s_nop 0
	v_mul_f32_e32 v130, 0x4b800000, v189
	v_cmp_gt_f32_e32 vcc, s11, v189
	v_cmp_gt_f32_e64 s[44:45], s11, v188
	s_nop 0
	v_cndmask_b32_e32 v130, v189, v130, vcc
	v_rsq_f32_e32 v130, v130
	s_nop 0
	v_mul_f32_e32 v131, 0x45800000, v130
	v_cndmask_b32_e32 v190, v130, v131, vcc
	v_lshlrev_b64 v[130:131], 6, v[178:179]
	v_lshl_add_u64 v[130:131], v[144:145], 0, v[130:131]
	v_pk_mul_f32 v[128:129], v[128:129], v[190:191] op_sel_hi:[1,0]
	v_pk_mul_f32 v[126:127], v[126:127], v[190:191] op_sel_hi:[1,0]
	v_mov_b64_e32 v[130:131], v[208:209]
	v_mov_b64_e32 v[132:133], v[210:211]
	v_mov_b32_e32 v150, v131
	v_mov_b32_e32 v151, v132
	v_mov_b32_e32 v131, v133
	v_pk_add_f32 v[150:151], v[150:151], v[130:131]
	v_lshlrev_b64 v[130:131], 6, v[158:159]
	v_lshl_add_u64 v[130:131], v[144:145], 0, v[130:131]
	v_mov_b64_e32 v[130:131], v[212:213]
	v_mov_b64_e32 v[132:133], v[214:215]
	v_mov_b32_e32 v152, v131
	v_mov_b32_e32 v153, v132
	v_mov_b32_e32 v131, v133
	v_pk_add_f32 v[130:131], v[152:153], v[130:131]
	v_mov_b32_e32 v133, v150
	v_mov_b32_e32 v132, v130
	v_mov_b32_e32 v150, v131
	v_pk_add_f32 v[130:131], v[132:133], v[150:151]
	ds_bpermute_b32 v133, v191, v131
	ds_bpermute_b32 v132, v191, v130
	s_waitcnt lgkmcnt(0)
	v_pk_add_f32 v[182:183], v[130:131], v[132:133]
	v_lshlrev_b64 v[130:131], 6, v[156:157]
	v_lshl_add_u64 v[130:131], v[144:145], 0, v[130:131]
	ds_bpermute_b32 v187, v0, v183
	ds_bpermute_b32 v186, v0, v182
	v_mov_b64_e32 v[130:131], v[216:217]
	v_mov_b64_e32 v[132:133], v[218:219]
	v_mov_b32_e32 v150, v131
	v_mov_b32_e32 v151, v132
	v_mov_b32_e32 v131, v133
	v_pk_add_f32 v[150:151], v[150:151], v[130:131]
	v_lshlrev_b64 v[130:131], 6, v[154:155]
	v_lshl_add_u64 v[130:131], v[144:145], 0, v[130:131]
	v_mov_b64_e32 v[130:131], v[220:221]
	v_mov_b64_e32 v[132:133], v[222:223]
	v_mov_b32_e32 v152, v131
	v_mov_b32_e32 v153, v132
	v_mov_b32_e32 v131, v133
	v_pk_add_f32 v[130:131], v[152:153], v[130:131]
	v_mov_b32_e32 v133, v150
	v_mov_b32_e32 v132, v130
	v_mov_b32_e32 v150, v131
	v_pk_add_f32 v[130:131], v[132:133], v[150:151]
	ds_bpermute_b32 v133, v191, v131
	ds_bpermute_b32 v132, v191, v130
	v_add_u32_e32 v152, 0xa0, v184
	v_ashrrev_i32_e32 v153, 31, v152
	s_waitcnt lgkmcnt(0)
	v_pk_add_f32 v[160:161], v[130:131], v[132:133]
	v_lshlrev_b64 v[130:131], 6, v[152:153]
	v_lshl_add_u64 v[130:131], v[144:145], 0, v[130:131]
	ds_bpermute_b32 v175, v0, v161
	ds_bpermute_b32 v174, v0, v160
	v_mov_b64_e32 v[130:131], v[224:225]
	v_mov_b64_e32 v[132:133], v[226:227]
	v_mov_b32_e32 v150, v131
	v_mov_b32_e32 v151, v132
	v_mov_b32_e32 v131, v133
	v_pk_add_f32 v[176:177], v[150:151], v[130:131]
	v_add_u32_e32 v150, 0xb0, v184
	v_ashrrev_i32_e32 v151, 31, v150
	v_lshlrev_b64 v[130:131], 6, v[150:151]
	v_lshl_add_u64 v[130:131], v[144:145], 0, v[130:131]
	v_mov_b64_e32 v[130:131], v[228:229]
	v_mov_b64_e32 v[132:133], v[230:231]
	v_mov_b32_e32 v170, v131
	v_mov_b32_e32 v171, v132
	v_mov_b32_e32 v131, v133
	v_pk_add_f32 v[130:131], v[170:171], v[130:131]
	v_mov_b32_e32 v133, v176
	v_mov_b32_e32 v132, v130
	v_mov_b32_e32 v176, v131
	v_pk_add_f32 v[130:131], v[132:133], v[176:177]
	ds_bpermute_b32 v133, v191, v131
	ds_bpermute_b32 v132, v191, v130
	v_pk_mul_f32 v[170:171], v[124:125], v[190:191] op_sel_hi:[1,0]
	v_pk_mul_f32 v[124:125], v[122:123], v[190:191] op_sel_hi:[1,0]
	v_cvt_pk_bf16_f32 v122, v126, v127
	v_cvt_pk_bf16_f32 v123, v128, v129
	s_waitcnt lgkmcnt(0)
	v_pk_add_f32 v[132:133], v[130:131], v[132:133]
	ds_bpermute_b32 v177, v0, v133
	ds_bpermute_b32 v176, v0, v132
	v_or_b32_e32 v130, s10, v194
	v_cmp_lt_i32_e64 s[42:43], s15, v130
	v_cvt_pk_bf16_f32 v124, v124, v125
	v_cvt_pk_bf16_f32 v125, v170, v171
	s_and_saveexec_b64 s[16:17], s[42:43]
	s_xor_b64 s[16:17], exec, s[16:17]
	s_cbranch_execz .LBB7_529
	s_cmpk_gt_u32 s13, 0x57f
	s_cbranch_scc1 .LBB7_529
	v_lshl_add_u64 v[126:127], s[94:95], 0, v[192:193]
	v_mov_b32_e32 v131, v1
	v_lshl_add_u64 v[126:127], v[130:131], 1, v[126:127]
	global_store_dwordx4 v[126:127], v[122:125], off offset:-768

.LBB7_806:
	s_lshl_b32 s13, s12, 5
	s_waitcnt vmcnt(0)
	s_barrier
	s_and_saveexec_b64 s[0:1], vcc
	s_cbranch_execz .LBB7_811
	s_and_b32 s3, s13, 0x7e0
	s_sub_i32 s3, 29, s3
	s_sub_i32 s4, s13, 30
	v_lshl_add_u32 v78, v150, 5, 0
	s_mov_b32 s5, 0x2aaaaaab
	s_movk_i32 s14, 0xfe80
	s_movk_i32 s15, 0x1a0
	v_cmp_gt_i32_e64 s[6:7], s15, v150
	v_mov_b32_e32 v79, v150
	v_mul_hi_i32 v80, v79, s5
	v_lshrrev_b32_e32 v81, 31, v80
	v_ashrrev_i32_e32 v80, 3, v80
	v_add_u32_e32 v80, v80, v81
	v_cmp_lt_i32_e64 s[42:43], s3, v80
	s_nop 1
	s_and_saveexec_b64 s[8:9], s[42:43]
	v_add_u32_e32 v82, s4, v80
	v_ashrrev_i32_e32 v83, 31, v82
	v_lshlrev_b64 v[82:83], 11, v[82:83]
	v_lshl_add_u64 v[82:83], s[44:45], 0, v[82:83]
	v_lshlrev_b32_e32 v84, 3, v79
	v_mad_i32_i24 v84, v80, s14, v84
	v_mov_b32_e32 v85, 0
	v_lshl_add_u64 v[82:83], v[84:85], 1, v[82:83]
	global_load_dwordx4 v[88:91], v[82:83], off offset:512
	global_load_dwordx4 v[92:95], v[82:83], off offset:1280
	s_or_b64 exec, exec, s[8:9]
	v_add_u32_e32 v79, 512, v150
	v_mul_hi_i32 v80, v79, s5
	v_lshrrev_b32_e32 v81, 31, v80
	v_ashrrev_i32_e32 v80, 3, v80
	v_add_u32_e32 v80, v80, v81
	v_cmp_lt_i32_e64 s[42:43], s3, v80
	s_nop 1
	s_and_saveexec_b64 s[8:9], s[42:43]
	v_add_u32_e32 v82, s4, v80
	v_ashrrev_i32_e32 v83, 31, v82
	v_lshlrev_b64 v[82:83], 11, v[82:83]
	v_lshl_add_u64 v[82:83], s[44:45], 0, v[82:83]
	v_lshlrev_b32_e32 v84, 3, v79
	v_mad_i32_i24 v84, v80, s14, v84
	v_mov_b32_e32 v85, 0
	v_lshl_add_u64 v[82:83], v[84:85], 1, v[82:83]
	global_load_dwordx4 v[96:99], v[82:83], off offset:512
	global_load_dwordx4 v[100:103], v[82:83], off offset:1280
	s_or_b64 exec, exec, s[8:9]
	v_add_u32_e32 v79, 1024, v150
	v_mul_hi_i32 v80, v79, s5
	v_lshrrev_b32_e32 v81, 31, v80
	v_ashrrev_i32_e32 v80, 3, v80
	v_add_u32_e32 v80, v80, v81
	v_cmp_lt_i32_e64 s[42:43], s3, v80
	s_nop 1
	s_and_saveexec_b64 s[8:9], s[42:43]
	v_add_u32_e32 v82, s4, v80
	v_ashrrev_i32_e32 v83, 31, v82
	v_lshlrev_b64 v[82:83], 11, v[82:83]
	v_lshl_add_u64 v[82:83], s[44:45], 0, v[82:83]
	v_lshlrev_b32_e32 v84, 3, v79
	v_mad_i32_i24 v84, v80, s14, v84
	v_mov_b32_e32 v85, 0
	v_lshl_add_u64 v[82:83], v[84:85], 1, v[82:83]
	global_load_dwordx4 v[104:107], v[82:83], off offset:512
	global_load_dwordx4 v[134:137], v[82:83], off offset:1280
	s_or_b64 exec, exec, s[8:9]
	v_add_u32_e32 v79, 1536, v150
	v_mul_hi_i32 v80, v79, s5
	v_lshrrev_b32_e32 v81, 31, v80
	v_ashrrev_i32_e32 v80, 3, v80
	v_add_u32_e32 v80, v80, v81
	v_cmp_lt_i32_e64 s[42:43], s3, v80
	s_nop 1
	s_and_saveexec_b64 s[8:9], s[42:43]
	v_add_u32_e32 v82, s4, v80
	v_ashrrev_i32_e32 v83, 31, v82
	v_lshlrev_b64 v[82:83], 11, v[82:83]
	v_lshl_add_u64 v[82:83], s[44:45], 0, v[82:83]
	v_lshlrev_b32_e32 v84, 3, v79
	v_mad_i32_i24 v84, v80, s14, v84
	v_mov_b32_e32 v85, 0
	v_lshl_add_u64 v[82:83], v[84:85], 1, v[82:83]
	global_load_dwordx4 v[138:141], v[82:83], off offset:512
	global_load_dwordx4 v[142:145], v[82:83], off offset:1280
	s_or_b64 exec, exec, s[8:9]
	v_add_u32_e32 v79, 2048, v150
	v_mul_hi_i32 v80, v79, s5
	v_lshrrev_b32_e32 v81, 31, v80
	v_ashrrev_i32_e32 v80, 3, v80
	v_add_u32_e32 v80, v80, v81
	v_cmp_lt_i32_e64 s[42:43], s3, v80
	s_nop 1
	s_and_saveexec_b64 s[8:9], s[42:43]
	v_add_u32_e32 v82, s4, v80
	v_ashrrev_i32_e32 v83, 31, v82
	v_lshlrev_b64 v[82:83], 11, v[82:83]
	v_lshl_add_u64 v[82:83], s[44:45], 0, v[82:83]
	v_lshlrev_b32_e32 v84, 3, v79
	v_mad_i32_i24 v84, v80, s14, v84
	v_mov_b32_e32 v85, 0
	v_lshl_add_u64 v[82:83], v[84:85], 1, v[82:83]
	global_load_dwordx4 v[146:149], v[82:83], off offset:512
	global_load_dwordx4 v[152:155], v[82:83], off offset:1280
	s_or_b64 exec, exec, s[8:9]
	v_add_u32_e32 v79, 2560, v150
	v_mul_hi_i32 v80, v79, s5
	v_lshrrev_b32_e32 v81, 31, v80
	v_ashrrev_i32_e32 v80, 3, v80
	v_add_u32_e32 v80, v80, v81
	v_cmp_lt_i32_e64 s[42:43], s3, v80
	s_nop 1
	s_and_b64 s[42:43], s[42:43], s[6:7]
	s_and_saveexec_b64 s[8:9], s[42:43]
	v_add_u32_e32 v82, s4, v80
	v_ashrrev_i32_e32 v83, 31, v82
	v_lshlrev_b64 v[82:83], 11, v[82:83]
	v_lshl_add_u64 v[82:83], s[44:45], 0, v[82:83]
	v_lshlrev_b32_e32 v84, 3, v79
	v_mad_i32_i24 v84, v80, s14, v84
	v_mov_b32_e32 v85, 0
	v_lshl_add_u64 v[82:83], v[84:85], 1, v[82:83]
	global_load_dwordx4 v[156:159], v[82:83], off offset:512
	global_load_dwordx4 v[170:173], v[82:83], off offset:1280
	s_or_b64 exec, exec, s[8:9]
	v_mov_b32_e32 v79, v150
	v_mul_hi_i32 v80, v79, s5
	v_lshrrev_b32_e32 v81, 31, v80
	v_ashrrev_i32_e32 v80, 3, v80
	v_add_u32_e32 v80, v80, v81
	v_cmp_lt_i32_e64 s[42:43], s3, v80
	s_nop 1
	v_mov_b64_e32 v[2:3], 0
	v_mov_b64_e32 v[4:5], 0
	v_mov_b64_e32 v[6:7], 0
	v_mov_b64_e32 v[8:9], 0
	s_waitcnt vmcnt(0)
	s_and_saveexec_b64 s[8:9], s[42:43]
	v_lshlrev_b32_e32 v2, 16, v92
	v_and_b32_e32 v3, 0xffff0000, v92
	v_lshlrev_b32_e32 v4, 16, v93
	v_and_b32_e32 v5, 0xffff0000, v93
	v_lshlrev_b32_e32 v6, 16, v94
	v_and_b32_e32 v7, 0xffff0000, v94
	v_lshlrev_b32_e32 v8, 16, v95
	v_and_b32_e32 v9, 0xffff0000, v95
	v_mul_f32_e32 v2, 0xbfb8aa3b, v2
	v_mul_f32_e32 v3, 0xbfb8aa3b, v3
	v_mul_f32_e32 v4, 0xbfb8aa3b, v4
	v_mul_f32_e32 v5, 0xbfb8aa3b, v5
	v_mul_f32_e32 v6, 0xbfb8aa3b, v6
	v_mul_f32_e32 v7, 0xbfb8aa3b, v7
	v_mul_f32_e32 v8, 0xbfb8aa3b, v8
	v_mul_f32_e32 v9, 0xbfb8aa3b, v9
	v_exp_f32_e32 v2, v2
	v_exp_f32_e32 v3, v3
	v_exp_f32_e32 v4, v4
	v_exp_f32_e32 v5, v5
	v_exp_f32_e32 v6, v6
	v_exp_f32_e32 v7, v7
	v_exp_f32_e32 v8, v8
	v_exp_f32_e32 v9, v9
	v_add_f32_e32 v2, 1.0, v2
	v_add_f32_e32 v3, 1.0, v3
	v_add_f32_e32 v4, 1.0, v4
	v_add_f32_e32 v5, 1.0, v5
	v_add_f32_e32 v6, 1.0, v6
	v_add_f32_e32 v7, 1.0, v7
	v_add_f32_e32 v8, 1.0, v8
	v_add_f32_e32 v9, 1.0, v9
	v_rcp_f32_e32 v2, v2
	v_rcp_f32_e32 v3, v3
	v_rcp_f32_e32 v4, v4
	v_rcp_f32_e32 v5, v5
	v_rcp_f32_e32 v6, v6
	v_rcp_f32_e32 v7, v7
	v_rcp_f32_e32 v8, v8
	v_rcp_f32_e32 v9, v9
	v_lshlrev_b32_e32 v80, 16, v88
	v_and_b32_e32 v81, 0xffff0000, v88
	v_lshlrev_b32_e32 v82, 16, v89
	v_and_b32_e32 v83, 0xffff0000, v89
	v_lshlrev_b32_e32 v84, 16, v90
	v_and_b32_e32 v85, 0xffff0000, v90
	v_lshlrev_b32_e32 v86, 16, v91
	v_and_b32_e32 v87, 0xffff0000, v91
	v_mul_f32_e32 v2, v2, v80
	v_mul_f32_e32 v3, v3, v81
	v_mul_f32_e32 v4, v4, v82
	v_mul_f32_e32 v5, v5, v83
	v_mul_f32_e32 v6, v6, v84
	v_mul_f32_e32 v7, v7, v85
	v_mul_f32_e32 v8, v8, v86
	v_mul_f32_e32 v9, v9, v87
	s_or_b64 exec, exec, s[8:9]
	ds_write_b128 v78, v[2:5]
	ds_write_b128 v78, v[6:9] offset:16
	v_add_u32_e32 v79, 512, v150
	v_mul_hi_i32 v80, v79, s5
	v_lshrrev_b32_e32 v81, 31, v80
	v_ashrrev_i32_e32 v80, 3, v80
	v_add_u32_e32 v80, v80, v81
	v_cmp_lt_i32_e64 s[42:43], s3, v80
	s_nop 1
	v_mov_b64_e32 v[2:3], 0
	v_mov_b64_e32 v[4:5], 0
	v_mov_b64_e32 v[6:7], 0
	v_mov_b64_e32 v[8:9], 0
	s_and_saveexec_b64 s[8:9], s[42:43]
	v_lshlrev_b32_e32 v2, 16, v100
	v_and_b32_e32 v3, 0xffff0000, v100
	v_lshlrev_b32_e32 v4, 16, v101
	v_and_b32_e32 v5, 0xffff0000, v101
	v_lshlrev_b32_e32 v6, 16, v102
	v_and_b32_e32 v7, 0xffff0000, v102
	v_lshlrev_b32_e32 v8, 16, v103
	v_and_b32_e32 v9, 0xffff0000, v103
	v_mul_f32_e32 v2, 0xbfb8aa3b, v2
	v_mul_f32_e32 v3, 0xbfb8aa3b, v3
	v_mul_f32_e32 v4, 0xbfb8aa3b, v4
	v_mul_f32_e32 v5, 0xbfb8aa3b, v5
	v_mul_f32_e32 v6, 0xbfb8aa3b, v6
	v_mul_f32_e32 v7, 0xbfb8aa3b, v7
	v_mul_f32_e32 v8, 0xbfb8aa3b, v8
	v_mul_f32_e32 v9, 0xbfb8aa3b, v9
	v_exp_f32_e32 v2, v2
	v_exp_f32_e32 v3, v3
	v_exp_f32_e32 v4, v4
	v_exp_f32_e32 v5, v5
	v_exp_f32_e32 v6, v6
	v_exp_f32_e32 v7, v7
	v_exp_f32_e32 v8, v8
	v_exp_f32_e32 v9, v9
	v_add_f32_e32 v2, 1.0, v2
	v_add_f32_e32 v3, 1.0, v3
	v_add_f32_e32 v4, 1.0, v4
	v_add_f32_e32 v5, 1.0, v5
	v_add_f32_e32 v6, 1.0, v6
	v_add_f32_e32 v7, 1.0, v7
	v_add_f32_e32 v8, 1.0, v8
	v_add_f32_e32 v9, 1.0, v9
	v_rcp_f32_e32 v2, v2
	v_rcp_f32_e32 v3, v3
	v_rcp_f32_e32 v4, v4
	v_rcp_f32_e32 v5, v5
	v_rcp_f32_e32 v6, v6
	v_rcp_f32_e32 v7, v7
	v_rcp_f32_e32 v8, v8
	v_rcp_f32_e32 v9, v9
	v_lshlrev_b32_e32 v80, 16, v96
	v_and_b32_e32 v81, 0xffff0000, v96
	v_lshlrev_b32_e32 v82, 16, v97
	v_and_b32_e32 v83, 0xffff0000, v97
	v_lshlrev_b32_e32 v84, 16, v98
	v_and_b32_e32 v85, 0xffff0000, v98
	v_lshlrev_b32_e32 v86, 16, v99
	v_and_b32_e32 v87, 0xffff0000, v99
	v_mul_f32_e32 v2, v2, v80
	v_mul_f32_e32 v3, v3, v81
	v_mul_f32_e32 v4, v4, v82
	v_mul_f32_e32 v5, v5, v83
	v_mul_f32_e32 v6, v6, v84
	v_mul_f32_e32 v7, v7, v85
	v_mul_f32_e32 v8, v8, v86
	v_mul_f32_e32 v9, v9, v87
	s_or_b64 exec, exec, s[8:9]
	ds_write_b128 v78, v[2:5] offset:16384
	ds_write_b128 v78, v[6:9] offset:16400
	v_add_u32_e32 v79, 1024, v150
	v_mul_hi_i32 v80, v79, s5
	v_lshrrev_b32_e32 v81, 31, v80
	v_ashrrev_i32_e32 v80, 3, v80
	v_add_u32_e32 v80, v80, v81
	v_cmp_lt_i32_e64 s[42:43], s3, v80
	s_nop 1
	v_mov_b64_e32 v[2:3], 0
	v_mov_b64_e32 v[4:5], 0
	v_mov_b64_e32 v[6:7], 0
	v_mov_b64_e32 v[8:9], 0
	s_and_saveexec_b64 s[8:9], s[42:43]
	v_lshlrev_b32_e32 v2, 16, v134
	v_and_b32_e32 v3, 0xffff0000, v134
	v_lshlrev_b32_e32 v4, 16, v135
	v_and_b32_e32 v5, 0xffff0000, v135
	v_lshlrev_b32_e32 v6, 16, v136
	v_and_b32_e32 v7, 0xffff0000, v136
	v_lshlrev_b32_e32 v8, 16, v137
	v_and_b32_e32 v9, 0xffff0000, v137
	v_mul_f32_e32 v2, 0xbfb8aa3b, v2
	v_mul_f32_e32 v3, 0xbfb8aa3b, v3
	v_mul_f32_e32 v4, 0xbfb8aa3b, v4
	v_mul_f32_e32 v5, 0xbfb8aa3b, v5
	v_mul_f32_e32 v6, 0xbfb8aa3b, v6
	v_mul_f32_e32 v7, 0xbfb8aa3b, v7
	v_mul_f32_e32 v8, 0xbfb8aa3b, v8
	v_mul_f32_e32 v9, 0xbfb8aa3b, v9
	v_exp_f32_e32 v2, v2
	v_exp_f32_e32 v3, v3
	v_exp_f32_e32 v4, v4
	v_exp_f32_e32 v5, v5
	v_exp_f32_e32 v6, v6
	v_exp_f32_e32 v7, v7
	v_exp_f32_e32 v8, v8
	v_exp_f32_e32 v9, v9
	v_add_f32_e32 v2, 1.0, v2
	v_add_f32_e32 v3, 1.0, v3
	v_add_f32_e32 v4, 1.0, v4
	v_add_f32_e32 v5, 1.0, v5
	v_add_f32_e32 v6, 1.0, v6
	v_add_f32_e32 v7, 1.0, v7
	v_add_f32_e32 v8, 1.0, v8
	v_add_f32_e32 v9, 1.0, v9
	v_rcp_f32_e32 v2, v2
	v_rcp_f32_e32 v3, v3
	v_rcp_f32_e32 v4, v4
	v_rcp_f32_e32 v5, v5
	v_rcp_f32_e32 v6, v6
	v_rcp_f32_e32 v7, v7
	v_rcp_f32_e32 v8, v8
	v_rcp_f32_e32 v9, v9
	v_lshlrev_b32_e32 v80, 16, v104
	v_and_b32_e32 v81, 0xffff0000, v104
	v_lshlrev_b32_e32 v82, 16, v105
	v_and_b32_e32 v83, 0xffff0000, v105
	v_lshlrev_b32_e32 v84, 16, v106
	v_and_b32_e32 v85, 0xffff0000, v106
	v_lshlrev_b32_e32 v86, 16, v107
	v_and_b32_e32 v87, 0xffff0000, v107
	v_mul_f32_e32 v2, v2, v80
	v_mul_f32_e32 v3, v3, v81
	v_mul_f32_e32 v4, v4, v82
	v_mul_f32_e32 v5, v5, v83
	v_mul_f32_e32 v6, v6, v84
	v_mul_f32_e32 v7, v7, v85
	v_mul_f32_e32 v8, v8, v86
	v_mul_f32_e32 v9, v9, v87
	s_or_b64 exec, exec, s[8:9]
	ds_write_b128 v78, v[2:5] offset:32768
	ds_write_b128 v78, v[6:9] offset:32784
	v_add_u32_e32 v79, 1536, v150
	v_mul_hi_i32 v80, v79, s5
	v_lshrrev_b32_e32 v81, 31, v80
	v_ashrrev_i32_e32 v80, 3, v80
	v_add_u32_e32 v80, v80, v81
	v_cmp_lt_i32_e64 s[42:43], s3, v80
	s_nop 1
	v_mov_b64_e32 v[2:3], 0
	v_mov_b64_e32 v[4:5], 0
	v_mov_b64_e32 v[6:7], 0
	v_mov_b64_e32 v[8:9], 0
	s_and_saveexec_b64 s[8:9], s[42:43]
	v_lshlrev_b32_e32 v2, 16, v142
	v_and_b32_e32 v3, 0xffff0000, v142
	v_lshlrev_b32_e32 v4, 16, v143
	v_and_b32_e32 v5, 0xffff0000, v143
	v_lshlrev_b32_e32 v6, 16, v144
	v_and_b32_e32 v7, 0xffff0000, v144
	v_lshlrev_b32_e32 v8, 16, v145
	v_and_b32_e32 v9, 0xffff0000, v145
	v_mul_f32_e32 v2, 0xbfb8aa3b, v2
	v_mul_f32_e32 v3, 0xbfb8aa3b, v3
	v_mul_f32_e32 v4, 0xbfb8aa3b, v4
	v_mul_f32_e32 v5, 0xbfb8aa3b, v5
	v_mul_f32_e32 v6, 0xbfb8aa3b, v6
	v_mul_f32_e32 v7, 0xbfb8aa3b, v7
	v_mul_f32_e32 v8, 0xbfb8aa3b, v8
	v_mul_f32_e32 v9, 0xbfb8aa3b, v9
	v_exp_f32_e32 v2, v2
	v_exp_f32_e32 v3, v3
	v_exp_f32_e32 v4, v4
	v_exp_f32_e32 v5, v5
	v_exp_f32_e32 v6, v6
	v_exp_f32_e32 v7, v7
	v_exp_f32_e32 v8, v8
	v_exp_f32_e32 v9, v9
	v_add_f32_e32 v2, 1.0, v2
	v_add_f32_e32 v3, 1.0, v3
	v_add_f32_e32 v4, 1.0, v4
	v_add_f32_e32 v5, 1.0, v5
	v_add_f32_e32 v6, 1.0, v6
	v_add_f32_e32 v7, 1.0, v7
	v_add_f32_e32 v8, 1.0, v8
	v_add_f32_e32 v9, 1.0, v9
	v_rcp_f32_e32 v2, v2
	v_rcp_f32_e32 v3, v3
	v_rcp_f32_e32 v4, v4
	v_rcp_f32_e32 v5, v5
	v_rcp_f32_e32 v6, v6
	v_rcp_f32_e32 v7, v7
	v_rcp_f32_e32 v8, v8
	v_rcp_f32_e32 v9, v9
	v_lshlrev_b32_e32 v80, 16, v138
	v_and_b32_e32 v81, 0xffff0000, v138
	v_lshlrev_b32_e32 v82, 16, v139
	v_and_b32_e32 v83, 0xffff0000, v139
	v_lshlrev_b32_e32 v84, 16, v140
	v_and_b32_e32 v85, 0xffff0000, v140
	v_lshlrev_b32_e32 v86, 16, v141
	v_and_b32_e32 v87, 0xffff0000, v141
	v_mul_f32_e32 v2, v2, v80
	v_mul_f32_e32 v3, v3, v81
	v_mul_f32_e32 v4, v4, v82
	v_mul_f32_e32 v5, v5, v83
	v_mul_f32_e32 v6, v6, v84
	v_mul_f32_e32 v7, v7, v85
	v_mul_f32_e32 v8, v8, v86
	v_mul_f32_e32 v9, v9, v87
	s_or_b64 exec, exec, s[8:9]
	ds_write_b128 v78, v[2:5] offset:49152
	ds_write_b128 v78, v[6:9] offset:49168
	v_add_u32_e32 v79, 2048, v150
	v_mul_hi_i32 v80, v79, s5
	v_lshrrev_b32_e32 v81, 31, v80
	v_ashrrev_i32_e32 v80, 3, v80
	v_add_u32_e32 v80, v80, v81
	v_cmp_lt_i32_e64 s[42:43], s3, v80
	s_nop 1
	v_mov_b64_e32 v[2:3], 0
	v_mov_b64_e32 v[4:5], 0
	v_mov_b64_e32 v[6:7], 0
	v_mov_b64_e32 v[8:9], 0
	s_and_saveexec_b64 s[8:9], s[42:43]
	v_lshlrev_b32_e32 v2, 16, v152
	v_and_b32_e32 v3, 0xffff0000, v152
	v_lshlrev_b32_e32 v4, 16, v153
	v_and_b32_e32 v5, 0xffff0000, v153
	v_lshlrev_b32_e32 v6, 16, v154
	v_and_b32_e32 v7, 0xffff0000, v154
	v_lshlrev_b32_e32 v8, 16, v155
	v_and_b32_e32 v9, 0xffff0000, v155
	v_mul_f32_e32 v2, 0xbfb8aa3b, v2
	v_mul_f32_e32 v3, 0xbfb8aa3b, v3
	v_mul_f32_e32 v4, 0xbfb8aa3b, v4
	v_mul_f32_e32 v5, 0xbfb8aa3b, v5
	v_mul_f32_e32 v6, 0xbfb8aa3b, v6
	v_mul_f32_e32 v7, 0xbfb8aa3b, v7
	v_mul_f32_e32 v8, 0xbfb8aa3b, v8
	v_mul_f32_e32 v9, 0xbfb8aa3b, v9
	v_exp_f32_e32 v2, v2
	v_exp_f32_e32 v3, v3
	v_exp_f32_e32 v4, v4
	v_exp_f32_e32 v5, v5
	v_exp_f32_e32 v6, v6
	v_exp_f32_e32 v7, v7
	v_exp_f32_e32 v8, v8
	v_exp_f32_e32 v9, v9
	v_add_f32_e32 v2, 1.0, v2
	v_add_f32_e32 v3, 1.0, v3
	v_add_f32_e32 v4, 1.0, v4
	v_add_f32_e32 v5, 1.0, v5
	v_add_f32_e32 v6, 1.0, v6
	v_add_f32_e32 v7, 1.0, v7
	v_add_f32_e32 v8, 1.0, v8
	v_add_f32_e32 v9, 1.0, v9
	v_rcp_f32_e32 v2, v2
	v_rcp_f32_e32 v3, v3
	v_rcp_f32_e32 v4, v4
	v_rcp_f32_e32 v5, v5
	v_rcp_f32_e32 v6, v6
	v_rcp_f32_e32 v7, v7
	v_rcp_f32_e32 v8, v8
	v_rcp_f32_e32 v9, v9
	v_lshlrev_b32_e32 v80, 16, v146
	v_and_b32_e32 v81, 0xffff0000, v146
	v_lshlrev_b32_e32 v82, 16, v147
	v_and_b32_e32 v83, 0xffff0000, v147
	v_lshlrev_b32_e32 v84, 16, v148
	v_and_b32_e32 v85, 0xffff0000, v148
	v_lshlrev_b32_e32 v86, 16, v149
	v_and_b32_e32 v87, 0xffff0000, v149
	v_mul_f32_e32 v2, v2, v80
	v_mul_f32_e32 v3, v3, v81
	v_mul_f32_e32 v4, v4, v82
	v_mul_f32_e32 v5, v5, v83
	v_mul_f32_e32 v6, v6, v84
	v_mul_f32_e32 v7, v7, v85
	v_mul_f32_e32 v8, v8, v86
	v_mul_f32_e32 v9, v9, v87
	s_or_b64 exec, exec, s[8:9]
	v_add_u32_e32 v79, 0x10000, v78
	ds_write_b128 v79, v[2:5]
	ds_write_b128 v79, v[6:9] offset:16
	v_add_u32_e32 v79, 2560, v150
	v_mul_hi_i32 v80, v79, s5
	v_lshrrev_b32_e32 v81, 31, v80
	v_ashrrev_i32_e32 v80, 3, v80
	v_add_u32_e32 v80, v80, v81
	v_cmp_lt_i32_e64 s[42:43], s3, v80
	s_nop 1
	s_and_b64 s[42:43], s[42:43], s[6:7]
	v_mov_b64_e32 v[2:3], 0
	v_mov_b64_e32 v[4:5], 0
	v_mov_b64_e32 v[6:7], 0
	v_mov_b64_e32 v[8:9], 0
	s_and_saveexec_b64 s[8:9], s[42:43]
	v_lshlrev_b32_e32 v2, 16, v170
	v_and_b32_e32 v3, 0xffff0000, v170
	v_lshlrev_b32_e32 v4, 16, v171
	v_and_b32_e32 v5, 0xffff0000, v171
	v_lshlrev_b32_e32 v6, 16, v172
	v_and_b32_e32 v7, 0xffff0000, v172
	v_lshlrev_b32_e32 v8, 16, v173
	v_and_b32_e32 v9, 0xffff0000, v173
	v_mul_f32_e32 v2, 0xbfb8aa3b, v2
	v_mul_f32_e32 v3, 0xbfb8aa3b, v3
	v_mul_f32_e32 v4, 0xbfb8aa3b, v4
	v_mul_f32_e32 v5, 0xbfb8aa3b, v5
	v_mul_f32_e32 v6, 0xbfb8aa3b, v6
	v_mul_f32_e32 v7, 0xbfb8aa3b, v7
	v_mul_f32_e32 v8, 0xbfb8aa3b, v8
	v_mul_f32_e32 v9, 0xbfb8aa3b, v9
	v_exp_f32_e32 v2, v2
	v_exp_f32_e32 v3, v3
	v_exp_f32_e32 v4, v4
	v_exp_f32_e32 v5, v5
	v_exp_f32_e32 v6, v6
	v_exp_f32_e32 v7, v7
	v_exp_f32_e32 v8, v8
	v_exp_f32_e32 v9, v9
	v_add_f32_e32 v2, 1.0, v2
	v_add_f32_e32 v3, 1.0, v3
	v_add_f32_e32 v4, 1.0, v4
	v_add_f32_e32 v5, 1.0, v5
	v_add_f32_e32 v6, 1.0, v6
	v_add_f32_e32 v7, 1.0, v7
	v_add_f32_e32 v8, 1.0, v8
	v_add_f32_e32 v9, 1.0, v9
	v_rcp_f32_e32 v2, v2
	v_rcp_f32_e32 v3, v3
	v_rcp_f32_e32 v4, v4
	v_rcp_f32_e32 v5, v5
	v_rcp_f32_e32 v6, v6
	v_rcp_f32_e32 v7, v7
	v_rcp_f32_e32 v8, v8
	v_rcp_f32_e32 v9, v9
	v_lshlrev_b32_e32 v80, 16, v156
	v_and_b32_e32 v81, 0xffff0000, v156
	v_lshlrev_b32_e32 v82, 16, v157
	v_and_b32_e32 v83, 0xffff0000, v157
	v_lshlrev_b32_e32 v84, 16, v158
	v_and_b32_e32 v85, 0xffff0000, v158
	v_lshlrev_b32_e32 v86, 16, v159
	v_and_b32_e32 v87, 0xffff0000, v159
	v_mul_f32_e32 v2, v2, v80
	v_mul_f32_e32 v3, v3, v81
	v_mul_f32_e32 v4, v4, v82
	v_mul_f32_e32 v5, v5, v83
	v_mul_f32_e32 v6, v6, v84
	v_mul_f32_e32 v7, v7, v85
	v_mul_f32_e32 v8, v8, v86
	v_mul_f32_e32 v9, v9, v87
	s_or_b64 exec, exec, s[8:9]
	s_and_saveexec_b64 s[8:9], s[6:7]
	v_add_u32_e32 v79, 0x14000, v78
	ds_write_b128 v79, v[2:5]
	ds_write_b128 v79, v[6:9] offset:16
	s_or_b64 exec, exec, s[8:9]

.LBB7_1199:
	v_lshl_add_u32 v190, s10, 8, v149
	v_ashrrev_i32_e32 v191, 31, v190
	v_lshlrev_b64 v[190:191], 6, v[190:191]
	v_lshl_add_u64 v[190:191], v[140:141], 0, v[190:191]
	global_load_dwordx4 v[204:207], v[190:191], off
	global_load_dwordx4 v[208:211], v[190:191], off offset:1024
	global_load_dwordx4 v[212:215], v[190:191], off offset:2048
	global_load_dwordx4 v[216:219], v[190:191], off offset:3072
	v_add_co_u32_e32 v190, vcc, 0x2000, v190
	s_nop 1
	v_addc_co_u32_e32 v191, vcc, 0, v191, vcc
	global_load_dwordx4 v[220:223], v[190:191], off
	global_load_dwordx4 v[224:227], v[190:191], off offset:1024
	global_load_dwordx4 v[228:231], v[190:191], off offset:2048
	global_load_dwordx4 v[232:235], v[190:191], off offset:3072
	v_and_b32_e32 v131, 64, v163
	v_xor_b32_e32 v130, 16, v163
	v_add_u32_e32 v131, 64, v131
	v_cmp_lt_i32_e32 vcc, v130, v131
	v_lshl_add_u32 v146, s10, 8, v149
	v_ashrrev_i32_e32 v147, 31, v146
	v_cndmask_b32_e32 v130, v163, v130, vcc
	v_lshlrev_b32_e32 v183, 2, v130
	v_xor_b32_e32 v130, 32, v163
	v_cmp_lt_i32_e32 vcc, v130, v131
	s_mov_b32 s10, 0x358637bd
	v_mov_b64_e32 v[178:179], s[10:11]
	v_cndmask_b32_e32 v130, v163, v130, vcc
	v_lshlrev_b32_e32 v175, 2, v130
	v_lshlrev_b64 v[130:131], 6, v[146:147]
	v_lshl_add_u64 v[130:131], v[140:141], 0, v[130:131]
	v_add_u32_e32 v180, 0x80, v146
	v_ashrrev_i32_e32 v181, 31, v180
	v_add_u32_e32 v176, 0x90, v146
	v_ashrrev_i32_e32 v177, 31, v176
	v_add_u32_e32 v186, 0xa0, v146
	v_ashrrev_i32_e32 v187, 31, v186
	v_add_u32_e32 v184, 0xb0, v146
	v_ashrrev_i32_e32 v185, 31, v184
	s_mov_b64 s[16:17], -1
	s_waitcnt vmcnt(0)
	v_mov_b64_e32 v[130:131], v[204:205]
	v_mov_b64_e32 v[132:133], v[206:207]
	v_mov_b32_e32 v150, v131
	v_mov_b32_e32 v151, v132
	v_mov_b32_e32 v131, v133
	v_pk_add_f32 v[156:157], v[150:151], v[130:131]
	v_or_b32_e32 v150, 16, v146
	v_ashrrev_i32_e32 v151, 31, v150
	v_lshlrev_b64 v[130:131], 6, v[150:151]
	v_lshl_add_u64 v[130:131], v[140:141], 0, v[130:131]
	v_mov_b64_e32 v[130:131], v[208:209]
	v_mov_b64_e32 v[132:133], v[210:211]
	v_mov_b32_e32 v158, v131
	v_mov_b32_e32 v159, v132
	v_mov_b32_e32 v131, v133
	v_pk_add_f32 v[130:131], v[158:159], v[130:131]
	v_mov_b32_e32 v133, v156
	v_mov_b32_e32 v132, v130
	v_mov_b32_e32 v156, v131
	v_pk_add_f32 v[130:131], v[132:133], v[156:157]
	ds_bpermute_b32 v133, v183, v131
	ds_bpermute_b32 v132, v183, v130
	v_or_b32_e32 v158, 32, v146
	v_ashrrev_i32_e32 v159, 31, v158
	s_waitcnt lgkmcnt(0)
	v_pk_add_f32 v[130:131], v[130:131], v[132:133]
	ds_bpermute_b32 v133, v175, v131
	ds_bpermute_b32 v132, v175, v130
	s_waitcnt lgkmcnt(0)
	v_pk_add_f32 v[130:131], v[130:131], v[132:133]
	s_nop 0
	v_pk_fma_f32 v[130:131], v[130:131], s[26:27], v[178:179] op_sel_hi:[1,0,0]
	s_nop 0
	v_mul_f32_e32 v132, 0x4b800000, v131
	v_cmp_gt_f32_e64 s[42:43], s11, v131
	v_cmp_gt_f32_e32 vcc, s11, v130
	s_nop 0
	v_cndmask_b32_e64 v131, v131, v132, s[42:43]
	v_rsq_f32_e32 v131, v131
	s_nop 0
	v_mul_f32_e32 v132, 0x45800000, v131
	v_cndmask_b32_e64 v152, v131, v132, s[42:43]
	v_mul_f32_e32 v131, 0x4b800000, v130
	v_cndmask_b32_e32 v130, v130, v131, vcc
	v_rsq_f32_e32 v130, v130
	v_pk_mul_f32 v[128:129], v[128:129], v[152:153] op_sel_hi:[1,0]
	v_pk_mul_f32 v[126:127], v[126:127], v[152:153] op_sel_hi:[1,0]
	v_pk_mul_f32 v[120:121], v[120:121], v[152:153] op_sel_hi:[1,0]
	v_mul_f32_e32 v131, 0x45800000, v130
	v_cndmask_b32_e32 v148, v130, v131, vcc
	v_lshlrev_b64 v[130:131], 6, v[158:159]
	v_lshl_add_u64 v[130:131], v[140:141], 0, v[130:131]
	v_pk_mul_f32 v[118:119], v[118:119], v[152:153] op_sel_hi:[1,0]
	v_pk_mul_f32 v[112:113], v[112:113], v[148:149] op_sel_hi:[1,0]
	v_pk_mul_f32 v[110:111], v[110:111], v[148:149] op_sel_hi:[1,0]
	v_pk_mul_f32 v[104:105], v[104:105], v[148:149] op_sel_hi:[1,0]
	v_pk_mul_f32 v[102:103], v[102:103], v[148:149] op_sel_hi:[1,0]
	v_mov_b64_e32 v[130:131], v[212:213]
	v_mov_b64_e32 v[132:133], v[214:215]
	v_mov_b32_e32 v156, v131
	v_mov_b32_e32 v157, v132
	v_mov_b32_e32 v131, v133
	v_pk_add_f32 v[170:171], v[156:157], v[130:131]
	v_or_b32_e32 v156, 48, v146
	v_ashrrev_i32_e32 v157, 31, v156
	v_lshlrev_b64 v[130:131], 6, v[156:157]
	v_lshl_add_u64 v[130:131], v[140:141], 0, v[130:131]
	v_lshlrev_b64 v[146:147], 11, v[146:147]
	v_mov_b64_e32 v[130:131], v[216:217]
	v_mov_b64_e32 v[132:133], v[218:219]
	v_mov_b32_e32 v172, v131
	v_mov_b32_e32 v173, v132
	v_mov_b32_e32 v131, v133
	v_pk_add_f32 v[130:131], v[172:173], v[130:131]
	v_mov_b32_e32 v133, v170
	v_mov_b32_e32 v132, v130
	v_mov_b32_e32 v170, v131
	v_pk_add_f32 v[130:131], v[132:133], v[170:171]
	ds_bpermute_b32 v133, v183, v131
	ds_bpermute_b32 v132, v183, v130
	s_waitcnt lgkmcnt(0)
	v_pk_add_f32 v[130:131], v[130:131], v[132:133]
	ds_bpermute_b32 v133, v175, v131
	ds_bpermute_b32 v132, v175, v130
	s_waitcnt lgkmcnt(0)
	v_pk_add_f32 v[130:131], v[130:131], v[132:133]
	s_nop 0
	v_pk_fma_f32 v[130:131], v[130:131], s[26:27], v[178:179] op_sel_hi:[1,0,0]
	s_nop 0
	v_mul_f32_e32 v132, 0x4b800000, v131
	v_cmp_gt_f32_e64 s[42:43], s11, v131
	v_cmp_gt_f32_e32 vcc, s11, v130
	s_nop 0
	v_cndmask_b32_e64 v131, v131, v132, s[42:43]
	v_rsq_f32_e32 v131, v131
	s_nop 0
	v_mul_f32_e32 v132, 0x45800000, v131
	v_cndmask_b32_e64 v174, v131, v132, s[42:43]
	v_mul_f32_e32 v131, 0x4b800000, v130
	v_cndmask_b32_e32 v130, v130, v131, vcc
	v_rsq_f32_e32 v130, v130
	v_pk_mul_f32 v[96:97], v[96:97], v[174:175] op_sel_hi:[1,0]
	v_pk_mul_f32 v[94:95], v[94:95], v[174:175] op_sel_hi:[1,0]
	v_pk_mul_f32 v[88:89], v[88:89], v[174:175] op_sel_hi:[1,0]
	v_mul_f32_e32 v131, 0x45800000, v130
	v_cndmask_b32_e32 v154, v130, v131, vcc
	v_lshlrev_b64 v[130:131], 6, v[180:181]
	v_lshl_add_u64 v[130:131], v[140:141], 0, v[130:131]
	v_pk_mul_f32 v[86:87], v[86:87], v[174:175] op_sel_hi:[1,0]
	v_pk_mul_f32 v[80:81], v[80:81], v[154:155] op_sel_hi:[1,0]
	v_pk_mul_f32 v[78:79], v[78:79], v[154:155] op_sel_hi:[1,0]
	v_pk_mul_f32 v[72:73], v[72:73], v[154:155] op_sel_hi:[1,0]
	v_pk_mul_f32 v[70:71], v[70:71], v[154:155] op_sel_hi:[1,0]
	v_mov_b64_e32 v[130:131], v[220:221]
	v_mov_b64_e32 v[132:133], v[222:223]
	v_mov_b32_e32 v170, v131
	v_mov_b32_e32 v171, v132
	v_mov_b32_e32 v131, v133
	v_pk_add_f32 v[170:171], v[170:171], v[130:131]
	v_lshlrev_b64 v[130:131], 6, v[176:177]
	v_lshl_add_u64 v[130:131], v[140:141], 0, v[130:131]
	v_mov_b64_e32 v[130:131], v[224:225]
	v_mov_b64_e32 v[132:133], v[226:227]
	v_mov_b32_e32 v172, v131
	v_mov_b32_e32 v173, v132
	v_mov_b32_e32 v131, v133
	v_pk_add_f32 v[130:131], v[172:173], v[130:131]
	v_mov_b32_e32 v133, v170
	v_mov_b32_e32 v132, v130
	v_mov_b32_e32 v170, v131
	v_pk_add_f32 v[130:131], v[132:133], v[170:171]
	ds_bpermute_b32 v133, v183, v131
	ds_bpermute_b32 v132, v183, v130
	v_lshl_add_u64 v[172:173], s[94:95], 0, v[146:147]
	s_waitcnt lgkmcnt(0)
	v_pk_add_f32 v[130:131], v[130:131], v[132:133]
	ds_bpermute_b32 v133, v175, v131
	ds_bpermute_b32 v132, v175, v130
	s_waitcnt lgkmcnt(0)
	v_pk_add_f32 v[130:131], v[130:131], v[132:133]
	s_nop 0
	v_pk_fma_f32 v[130:131], v[130:131], s[26:27], v[178:179] op_sel_hi:[1,0,0]
	s_nop 0
	v_mul_f32_e32 v132, 0x4b800000, v131
	v_cmp_gt_f32_e64 s[42:43], s11, v131
	v_cmp_gt_f32_e32 vcc, s11, v130
	s_nop 0
	v_cndmask_b32_e64 v131, v131, v132, s[42:43]
	v_rsq_f32_e32 v131, v131
	s_nop 0
	v_mul_f32_e32 v132, 0x45800000, v131
	v_cndmask_b32_e64 v182, v131, v132, s[42:43]
	v_mul_f32_e32 v131, 0x4b800000, v130
	v_cndmask_b32_e32 v130, v130, v131, vcc
	v_rsq_f32_e32 v130, v130
	v_pk_mul_f32 v[64:65], v[64:65], v[182:183] op_sel_hi:[1,0]
	v_pk_mul_f32 v[62:63], v[62:63], v[182:183] op_sel_hi:[1,0]
	v_pk_mul_f32 v[56:57], v[56:57], v[182:183] op_sel_hi:[1,0]
	v_mul_f32_e32 v131, 0x45800000, v130
	v_cndmask_b32_e32 v160, v130, v131, vcc
	v_lshlrev_b64 v[130:131], 6, v[186:187]
	v_lshl_add_u64 v[130:131], v[140:141], 0, v[130:131]
	v_pk_mul_f32 v[54:55], v[54:55], v[182:183] op_sel_hi:[1,0]
	v_pk_mul_f32 v[48:49], v[48:49], v[160:161] op_sel_hi:[1,0]
	v_pk_mul_f32 v[46:47], v[46:47], v[160:161] op_sel_hi:[1,0]
	v_pk_mul_f32 v[40:41], v[40:41], v[160:161] op_sel_hi:[1,0]
	v_pk_mul_f32 v[38:39], v[38:39], v[160:161] op_sel_hi:[1,0]
	v_mov_b64_e32 v[130:131], v[228:229]
	v_mov_b64_e32 v[132:133], v[230:231]
	v_mov_b32_e32 v170, v131
	v_mov_b32_e32 v171, v132
	v_mov_b32_e32 v131, v133
	v_pk_add_f32 v[188:189], v[170:171], v[130:131]
	v_lshlrev_b64 v[130:131], 6, v[184:185]
	v_lshl_add_u64 v[130:131], v[140:141], 0, v[130:131]
	v_mov_b64_e32 v[130:131], v[232:233]
	v_mov_b64_e32 v[132:133], v[234:235]
	v_mov_b32_e32 v170, v131
	v_mov_b32_e32 v171, v132
	v_mov_b32_e32 v131, v133
	v_pk_add_f32 v[130:131], v[170:171], v[130:131]
	v_lshl_or_b32 v170, s38, 8, v155
	v_mov_b32_e32 v132, v130
	v_mov_b32_e32 v133, v188
	v_mov_b32_e32 v188, v131
	v_ashrrev_i32_e32 v171, 31, v170
	v_pk_add_f32 v[130:131], v[132:133], v[188:189]
	v_lshlrev_b64 v[146:147], 1, v[170:171]
	ds_bpermute_b32 v133, v183, v131
	ds_bpermute_b32 v132, v183, v130
	v_lshl_add_u64 v[170:171], v[172:173], 0, v[146:147]
	v_pk_mul_f32 v[172:173], v[124:125], v[152:153] op_sel_hi:[1,0]
	v_pk_mul_f32 v[124:125], v[122:123], v[152:153] op_sel_hi:[1,0]
	v_cvt_pk_bf16_f32 v122, v126, v127
	v_cvt_pk_bf16_f32 v123, v128, v129
	s_waitcnt lgkmcnt(0)
	v_pk_add_f32 v[130:131], v[130:131], v[132:133]
	v_cvt_pk_bf16_f32 v124, v124, v125
	v_cvt_pk_bf16_f32 v125, v172, v173
	global_store_dwordx4 v[170:171], v[122:125], off
	ds_bpermute_b32 v133, v175, v131
	ds_bpermute_b32 v132, v175, v130
	v_pk_mul_f32 v[122:123], v[116:117], v[152:153] op_sel_hi:[1,0]
	v_pk_mul_f32 v[116:117], v[114:115], v[152:153] op_sel_hi:[1,0]
	v_cvt_pk_bf16_f32 v114, v118, v119
	v_cvt_pk_bf16_f32 v115, v120, v121
	s_waitcnt lgkmcnt(0)
	v_pk_add_f32 v[130:131], v[130:131], v[132:133]
	v_cvt_pk_bf16_f32 v116, v116, v117
	v_cvt_pk_bf16_f32 v117, v122, v123
	global_store_dwordx4 v[170:171], v[114:117], off offset:256
	v_pk_fma_f32 v[130:131], v[130:131], s[26:27], v[178:179] op_sel_hi:[1,0,0]
	s_nop 0
	v_lshlrev_b64 v[114:115], 11, v[150:151]
	v_lshl_add_u64 v[114:115], s[94:95], 0, v[114:115]
	v_lshl_add_u64 v[114:115], v[114:115], 0, v[146:147]
	v_pk_mul_f32 v[116:117], v[108:109], v[148:149] op_sel_hi:[1,0]
	v_pk_mul_f32 v[108:109], v[106:107], v[148:149] op_sel_hi:[1,0]
	v_cvt_pk_bf16_f32 v106, v110, v111
	v_cvt_pk_bf16_f32 v107, v112, v113
	v_mul_f32_e32 v132, 0x4b800000, v131
	v_cvt_pk_bf16_f32 v108, v108, v109
	v_cvt_pk_bf16_f32 v109, v116, v117
	global_store_dwordx4 v[114:115], v[106:109], off
	v_cmp_gt_f32_e64 s[42:43], s11, v131
	v_cmp_gt_f32_e32 vcc, s11, v130
	v_pk_mul_f32 v[106:107], v[100:101], v[148:149] op_sel_hi:[1,0]
	v_pk_mul_f32 v[100:101], v[98:99], v[148:149] op_sel_hi:[1,0]
	v_cvt_pk_bf16_f32 v98, v102, v103
	v_cvt_pk_bf16_f32 v99, v104, v105
	v_cndmask_b32_e64 v131, v131, v132, s[42:43]
	v_cvt_pk_bf16_f32 v100, v100, v101
	v_cvt_pk_bf16_f32 v101, v106, v107
	global_store_dwordx4 v[114:115], v[98:101], off offset:256
	v_rsq_f32_e32 v131, v131
	s_nop 0
	v_lshlrev_b64 v[98:99], 11, v[158:159]
	v_lshl_add_u64 v[98:99], s[94:95], 0, v[98:99]
	v_lshl_add_u64 v[98:99], v[98:99], 0, v[146:147]
	v_pk_mul_f32 v[100:101], v[92:93], v[174:175] op_sel_hi:[1,0]
	v_pk_mul_f32 v[92:93], v[90:91], v[174:175] op_sel_hi:[1,0]
	v_cvt_pk_bf16_f32 v90, v94, v95
	v_cvt_pk_bf16_f32 v91, v96, v97
	v_mul_f32_e32 v132, 0x45800000, v131
	v_cvt_pk_bf16_f32 v92, v92, v93
	v_cvt_pk_bf16_f32 v93, v100, v101
	global_store_dwordx4 v[98:99], v[90:93], off
	v_cndmask_b32_e64 v132, v131, v132, s[42:43]
	v_mul_f32_e32 v131, 0x4b800000, v130
	v_pk_mul_f32 v[90:91], v[84:85], v[174:175] op_sel_hi:[1,0]
	v_pk_mul_f32 v[84:85], v[82:83], v[174:175] op_sel_hi:[1,0]
	v_cvt_pk_bf16_f32 v82, v86, v87
	v_cvt_pk_bf16_f32 v83, v88, v89
	v_cndmask_b32_e32 v130, v130, v131, vcc
	v_cvt_pk_bf16_f32 v84, v84, v85
	v_cvt_pk_bf16_f32 v85, v90, v91
	global_store_dwordx4 v[98:99], v[82:85], off offset:256
	v_rsq_f32_e32 v130, v130
	v_pk_mul_f32 v[32:33], v[32:33], v[132:133] op_sel_hi:[1,0]
	v_lshlrev_b64 v[82:83], 11, v[156:157]
	v_lshl_add_u64 v[82:83], s[94:95], 0, v[82:83]
	v_lshl_add_u64 v[82:83], v[82:83], 0, v[146:147]
	v_pk_mul_f32 v[84:85], v[76:77], v[154:155] op_sel_hi:[1,0]
	v_pk_mul_f32 v[76:77], v[74:75], v[154:155] op_sel_hi:[1,0]
	v_cvt_pk_bf16_f32 v74, v78, v79
	v_cvt_pk_bf16_f32 v75, v80, v81
	v_pk_mul_f32 v[30:31], v[30:31], v[132:133] op_sel_hi:[1,0]
	v_cvt_pk_bf16_f32 v76, v76, v77
	v_cvt_pk_bf16_f32 v77, v84, v85
	global_store_dwordx4 v[82:83], v[74:77], off
	v_pk_mul_f32 v[24:25], v[24:25], v[132:133] op_sel_hi:[1,0]
	v_pk_mul_f32 v[22:23], v[22:23], v[132:133] op_sel_hi:[1,0]
	v_pk_mul_f32 v[74:75], v[68:69], v[154:155] op_sel_hi:[1,0]
	v_pk_mul_f32 v[68:69], v[66:67], v[154:155] op_sel_hi:[1,0]
	v_cvt_pk_bf16_f32 v66, v70, v71
	v_cvt_pk_bf16_f32 v67, v72, v73
	v_mul_f32_e32 v131, 0x45800000, v130
	v_cvt_pk_bf16_f32 v68, v68, v69
	v_cvt_pk_bf16_f32 v69, v74, v75
	global_store_dwordx4 v[82:83], v[66:69], off offset:256
	v_cndmask_b32_e32 v130, v130, v131, vcc
	v_pk_mul_f32 v[16:17], v[16:17], v[130:131] op_sel_hi:[1,0]
	v_lshlrev_b64 v[66:67], 11, v[180:181]
	v_lshl_add_u64 v[66:67], s[94:95], 0, v[66:67]
	v_lshl_add_u64 v[66:67], v[66:67], 0, v[146:147]
	v_pk_mul_f32 v[68:69], v[60:61], v[182:183] op_sel_hi:[1,0]
	v_pk_mul_f32 v[60:61], v[58:59], v[182:183] op_sel_hi:[1,0]
	v_cvt_pk_bf16_f32 v58, v62, v63
	v_cvt_pk_bf16_f32 v59, v64, v65
	v_pk_mul_f32 v[14:15], v[14:15], v[130:131] op_sel_hi:[1,0]
	v_cvt_pk_bf16_f32 v60, v60, v61
	v_cvt_pk_bf16_f32 v61, v68, v69
	global_store_dwordx4 v[66:67], v[58:61], off
	v_pk_mul_f32 v[8:9], v[8:9], v[130:131] op_sel_hi:[1,0]
	v_pk_mul_f32 v[6:7], v[6:7], v[130:131] op_sel_hi:[1,0]
	v_pk_mul_f32 v[58:59], v[52:53], v[182:183] op_sel_hi:[1,0]
	v_pk_mul_f32 v[52:53], v[50:51], v[182:183] op_sel_hi:[1,0]
	v_cvt_pk_bf16_f32 v50, v54, v55
	v_cvt_pk_bf16_f32 v51, v56, v57
	s_andn2_b64 vcc, exec, s[40:41]
	v_cvt_pk_bf16_f32 v52, v52, v53
	v_cvt_pk_bf16_f32 v53, v58, v59
	global_store_dwordx4 v[66:67], v[50:53], off offset:256
	s_nop 1
	v_lshlrev_b64 v[50:51], 11, v[176:177]
	v_lshl_add_u64 v[50:51], s[94:95], 0, v[50:51]
	v_lshl_add_u64 v[50:51], v[50:51], 0, v[146:147]
	v_pk_mul_f32 v[52:53], v[44:45], v[160:161] op_sel_hi:[1,0]
	v_pk_mul_f32 v[44:45], v[42:43], v[160:161] op_sel_hi:[1,0]
	v_cvt_pk_bf16_f32 v42, v46, v47
	v_cvt_pk_bf16_f32 v43, v48, v49
	s_nop 0
	v_cvt_pk_bf16_f32 v44, v44, v45
	v_cvt_pk_bf16_f32 v45, v52, v53
	global_store_dwordx4 v[50:51], v[42:45], off
	s_nop 1
	v_pk_mul_f32 v[42:43], v[36:37], v[160:161] op_sel_hi:[1,0]
	v_pk_mul_f32 v[36:37], v[34:35], v[160:161] op_sel_hi:[1,0]
	v_cvt_pk_bf16_f32 v34, v38, v39
	v_cvt_pk_bf16_f32 v35, v40, v41
	s_nop 0
	v_cvt_pk_bf16_f32 v36, v36, v37
	v_cvt_pk_bf16_f32 v37, v42, v43
	global_store_dwordx4 v[50:51], v[34:37], off offset:256
	s_nop 1
	v_lshlrev_b64 v[34:35], 11, v[186:187]
	v_lshl_add_u64 v[34:35], s[94:95], 0, v[34:35]
	v_lshl_add_u64 v[34:35], v[34:35], 0, v[146:147]
	v_pk_mul_f32 v[36:37], v[28:29], v[132:133] op_sel_hi:[1,0]
	v_pk_mul_f32 v[28:29], v[26:27], v[132:133] op_sel_hi:[1,0]
	v_cvt_pk_bf16_f32 v26, v30, v31
	v_cvt_pk_bf16_f32 v27, v32, v33
	s_nop 0
	v_cvt_pk_bf16_f32 v28, v28, v29
	v_cvt_pk_bf16_f32 v29, v36, v37
	global_store_dwordx4 v[34:35], v[26:29], off
	s_nop 1
	v_pk_mul_f32 v[26:27], v[20:21], v[132:133] op_sel_hi:[1,0]
	v_pk_mul_f32 v[20:21], v[18:19], v[132:133] op_sel_hi:[1,0]
	v_cvt_pk_bf16_f32 v18, v22, v23
	v_cvt_pk_bf16_f32 v19, v24, v25
	s_nop 0
	v_cvt_pk_bf16_f32 v20, v20, v21
	v_cvt_pk_bf16_f32 v21, v26, v27
	global_store_dwordx4 v[34:35], v[18:21], off offset:256
	s_nop 1
	v_lshlrev_b64 v[18:19], 11, v[184:185]
	v_lshl_add_u64 v[18:19], s[94:95], 0, v[18:19]
	v_lshl_add_u64 v[18:19], v[18:19], 0, v[146:147]
	v_pk_mul_f32 v[20:21], v[12:13], v[130:131] op_sel_hi:[1,0]
	v_pk_mul_f32 v[12:13], v[10:11], v[130:131] op_sel_hi:[1,0]
	v_cvt_pk_bf16_f32 v10, v14, v15
	v_cvt_pk_bf16_f32 v11, v16, v17
	s_nop 0
	v_cvt_pk_bf16_f32 v12, v12, v13
	v_cvt_pk_bf16_f32 v13, v20, v21
	global_store_dwordx4 v[18:19], v[10:13], off
	s_nop 1
	v_pk_mul_f32 v[10:11], v[4:5], v[130:131] op_sel_hi:[1,0]
	v_pk_mul_f32 v[4:5], v[2:3], v[130:131] op_sel_hi:[1,0]
	v_cvt_pk_bf16_f32 v2, v6, v7
	v_cvt_pk_bf16_f32 v3, v8, v9
	s_nop 0
	v_cvt_pk_bf16_f32 v4, v4, v5
	v_cvt_pk_bf16_f32 v5, v10, v11
	global_store_dwordx4 v[18:19], v[2:5], off offset:256
	s_cbranch_vccnz .LBB7_1187
	s_andn2_b64 vcc, exec, s[0:1]
	s_cbranch_vccnz .LBB7_1186
	s_barrier
	s_branch .LBB7_1186
